# entry cooperative grid.sync replaced by device-memory counter barrier; first-barrier census loads issued together
# speedup vs baseline: 1.0038x; 1.0022x over previous
.LBB0_10:
	s_or_b64 exec, exec, s[6:7]
	v_lshrrev_b32_e32 v2, 20, v0
	v_lshrrev_b32_e32 v0, 10, v0
	v_or_b32_e32 v0, v0, v2
	s_movk_i32 s3, 0x3ff
	v_and_or_b32 v0, v0, s3, v1
	v_cmp_eq_u32_e64 s[4:5], 0, v0
	s_waitcnt lgkmcnt(0)
	s_barrier
	s_barrier
	s_and_saveexec_b64 s[6:7], s[4:5]
	s_cbranch_execz .LBB0_20
	s_waitcnt vmcnt(0)
	v_readlane_b32 s0, v255, 0
	v_readlane_b32 s1, v255, 1
	v_readlane_b32 s3, v255, 2
	v_mov_b32_e32 v2, 0x1f85000
	v_mov_b32_e32 v3, 1
	s_nop 4
	global_atomic_add v2, v3, s[0:1]
.Lgs_poll:
	global_load_dword v0, v2, s[0:1] sc1
	s_waitcnt vmcnt(0)
	v_cmp_gt_u32_e64 s[4:5], s3, v0
	s_and_b64 s[4:5], s[4:5], exec
	s_cbranch_scc0 .Lgs_done
	s_sleep 1
	s_branch .Lgs_poll

.LBB0_203:
	s_mul_hi_i32 s2, s26, 0xd1745d17
	s_lshr_b32 s3, s2, 31
	s_ashr_i32 s20, s2, 2
	s_mul_hi_i32 s2, s26, 0x2e8ba2e9
	s_add_i32 s20, s20, s3
	s_lshr_b32 s3, s2, 31
	s_ashr_i32 s2, s2, 2
	s_add_i32 s2, s2, s3
	s_mul_i32 s2, s2, 22
	s_sub_i32 s19, s26, s2
	v_lshl_or_b32 v64, s19, 7, v92
	v_ashrrev_i32_e32 v65, 31, v64
	v_add_u32_e32 v98, 0xb00, v64
	v_lshlrev_b64 v[66:67], 2, v[64:65]
	v_lshl_add_u64 v[0:1], s[6:7], 0, v[66:67]
	v_lshlrev_b64 v[68:69], 2, v[98:99]
	s_add_i32 s22, s20, 0x107
	v_lshl_add_u64 v[2:3], s[6:7], 0, v[68:69]
	v_lshl_add_u64 v[4:5], s[10:11], 0, v[66:67]
	v_lshl_add_u64 v[6:7], s[10:11], 0, v[68:69]
	global_load_dwordx2 v[70:71], v[0:1], off
	global_load_dwordx2 v[72:73], v[2:3], off
	global_load_dwordx2 v[74:75], v[4:5], off
	global_load_dwordx2 v[76:77], v[6:7], off
	v_lshl_add_u64 v[0:1], s[12:13], 0, v[66:67]
	s_lshl_b32 s21, s22, 7
	v_lshl_add_u64 v[2:3], s[12:13], 0, v[68:69]
	global_load_dwordx2 v[78:79], v[0:1], off
	global_load_dwordx2 v[80:81], v[2:3], off
	v_or_b32_e32 v0, s21, v194
	v_mov_b32_e32 v1, v99
	v_lshlrev_b64 v[0:1], 7, v[0:1]
	v_lshl_add_u64 v[4:5], s[8:9], 0, v[0:1]
	s_waitcnt vmcnt(0)
	v_add_co_u32_e32 v24, vcc, s33, v4
	v_lshl_add_u64 v[0:1], v[4:5], 0, s[74:75]
	s_nop 0
	v_addc_co_u32_e32 v25, vcc, 0, v5, vcc
	global_load_dwordx4 v[20:23], v[4:5], off offset:48
	global_load_dwordx4 v[36:39], v[4:5], off offset:32
	global_load_dwordx4 v[48:51], v[4:5], off offset:16
	global_load_dwordx4 v[56:59], v[4:5], off
	global_load_dwordx4 v[60:63], v[24:25], off
	global_load_dwordx4 v[28:31], v[0:1], off offset:48
	global_load_dwordx4 v[44:47], v[0:1], off offset:32
	global_load_dwordx4 v[52:55], v[0:1], off offset:16
	s_nop 0
	global_load_dwordx4 v[0:3], v[4:5], off offset:112
	global_load_dwordx4 v[8:11], v[4:5], off offset:96
	global_load_dwordx4 v[16:19], v[4:5], off offset:80
	global_load_dwordx4 v[32:35], v[4:5], off offset:64
	s_mov_b64 s[2:3], 0x2040
	v_lshl_add_u64 v[26:27], v[4:5], 0, s[2:3]
	global_load_dwordx4 v[4:7], v[26:27], off offset:48
	global_load_dwordx4 v[12:15], v[26:27], off offset:32
	global_load_dwordx4 v[40:43], v[24:25], off offset:64
	s_nop 0
	global_load_dwordx4 v[24:27], v[26:27], off offset:16
	s_and_b32 s18, s22, 63
	s_cmp_lg_u32 s18, 0
	s_cselect_b64 s[2:3], -1, 0
	s_cmpk_gt_i32 s26, 0xaf
	s_cselect_b64 s[14:15], -1, 0
	s_cmpk_lt_i32 s26, 0xb0
	s_cselect_b64 s[16:17], -1, 0
	s_and_b64 s[24:25], s[14:15], s[2:3]
	v_cndmask_b32_e64 v82, 0, 1, s[24:25]
	v_cmp_ne_u32_e64 s[2:3], 1, v82
	s_andn2_b64 vcc, exec, s[24:25]
	v_mov_b32_e32 v82, 0
	s_cbranch_vccnz .LBB0_205
	v_add_u32_e32 v82, s21, v93
	v_ashrrev_i32_e32 v83, 31, v82
	v_lshlrev_b64 v[82:83], 7, v[82:83]
	v_lshl_add_u64 v[90:91], s[8:9], 0, v[82:83]
	global_load_dwordx4 v[82:85], v[90:91], off offset:48
	global_load_dwordx4 v[86:89], v[90:91], off offset:32
	global_load_dwordx4 v[100:103], v[90:91], off
	global_load_dwordx4 v[104:107], v[90:91], off offset:16
	s_waitcnt vmcnt(3)
	v_add_f32_e32 v112, v82, v83
	v_add_f32_e32 v114, v84, v85
	s_waitcnt vmcnt(1)
	v_mov_b32_e32 v108, v100
	s_waitcnt vmcnt(0)
	v_mov_b32_e32 v109, v104
	v_mov_b32_e32 v104, v101
	v_pk_add_f32 v[100:101], v[108:109], v[104:105]
	v_mov_b32_e32 v104, v102
	v_mov_b32_e32 v105, v106
	v_mov_b32_e32 v106, v103
	v_pk_add_f32 v[102:103], v[104:105], v[106:107]
	s_nop 0
	v_pk_add_f32 v[100:101], v[100:101], v[102:103]
	s_nop 0
	v_add_f32_e32 v97, 0, v100
	v_add_f32_e32 v108, v97, v101
	v_mov_b32_e32 v100, v87
	v_mov_b32_e32 v101, v88
	v_mov_b32_e32 v87, v89
	v_pk_add_f32 v[86:87], v[100:101], v[86:87]
	s_nop 0
	v_pk_add_f32 v[110:111], v[86:87], v[86:87] op_sel:[0,1] op_sel_hi:[1,0]
	global_load_dwordx4 v[82:85], v[90:91], off offset:112
	global_load_dwordx4 v[86:89], v[90:91], off offset:96
	global_load_dwordx4 v[100:103], v[90:91], off offset:80
	global_load_dwordx4 v[104:107], v[90:91], off offset:64
	s_waitcnt vmcnt(2)
	v_add_f32_e32 v86, v86, v87
	v_add_f32_e32 v88, v88, v89
	s_waitcnt vmcnt(0)
	v_mov_b32_e32 v109, v104
	v_mov_b32_e32 v111, v105
	v_mov_b32_e32 v113, v106
	v_mov_b32_e32 v115, v107
	v_pk_add_f32 v[90:91], v[108:109], v[110:111]
	v_pk_add_f32 v[104:105], v[112:113], v[114:115]
	v_mov_b32_e32 v87, v84
	v_pk_add_f32 v[90:91], v[90:91], v[104:105]
	v_mov_b32_e32 v104, v101
	v_mov_b32_e32 v105, v102
	v_mov_b32_e32 v101, v103
	v_pk_add_f32 v[100:101], v[104:105], v[100:101]
	v_pk_add_f32 v[90:91], v[90:91], v[90:91] op_sel:[0,1] op_sel_hi:[1,0]
	v_pk_add_f32 v[100:101], v[100:101], v[100:101] op_sel:[0,1] op_sel_hi:[1,0]
	v_mov_b32_e32 v91, v82
	v_mov_b32_e32 v101, v83
	v_mov_b32_e32 v89, v85
	v_pk_add_f32 v[82:83], v[90:91], v[100:101]
	v_pk_add_f32 v[84:85], v[86:87], v[88:89]
	s_nop 0
	v_pk_add_f32 v[82:83], v[82:83], v[84:85]
	s_nop 0
	v_add_f32_e32 v82, v82, v83
	v_fmamk_f32 v82, v82, 0x3a800000, v206
	v_rsq_f32_e32 v82, v82

.LBB0_1168:
	s_waitcnt lgkmcnt(0)
	v_mov_b64_e32 v[20:21], s[4:5]
	flat_load_dword v0, v[20:21] sc1
	v_mov_b64_e32 v[22:23], s[6:7]
	flat_load_dword v1, v[22:23] sc1
	v_mov_b64_e32 v[20:21], s[8:9]
	flat_load_dword v2, v[20:21] sc1
	v_mov_b64_e32 v[22:23], s[10:11]
	flat_load_dword v3, v[22:23] sc1
	v_mov_b64_e32 v[20:21], s[12:13]
	flat_load_dword v4, v[20:21] sc1
	v_mov_b64_e32 v[22:23], s[14:15]
	flat_load_dword v5, v[22:23] sc1
	v_mov_b64_e32 v[20:21], s[16:17]
	flat_load_dword v6, v[20:21] sc1
	v_mov_b64_e32 v[22:23], s[18:19]
	flat_load_dword v7, v[22:23] sc1
	v_mov_b64_e32 v[20:21], s[20:21]
	flat_load_dword v8, v[20:21] sc1
	v_mov_b64_e32 v[22:23], s[22:23]
	flat_load_dword v9, v[22:23] sc1
	v_mov_b64_e32 v[20:21], s[24:25]
	flat_load_dword v10, v[20:21] sc1
	v_mov_b64_e32 v[22:23], s[26:27]
	flat_load_dword v11, v[22:23] sc1
	v_mov_b64_e32 v[20:21], s[28:29]
	flat_load_dword v12, v[20:21] sc1
	v_mov_b64_e32 v[22:23], s[30:31]
	flat_load_dword v13, v[22:23] sc1
	v_mov_b64_e32 v[20:21], s[34:35]
	flat_load_dword v14, v[20:21] sc1
	v_mov_b64_e32 v[22:23], s[36:37]
	flat_load_dword v15, v[22:23] sc1
	s_or_b64 s[44:45], s[44:45], exec
	s_or_b64 s[42:43], s[42:43], exec
	s_waitcnt vmcnt(0) lgkmcnt(0)
	v_add_u32_e32 v16, v1, v0
	v_add_u32_e32 v16, v16, v2
	v_add_u32_e32 v16, v16, v3
	v_add_u32_e32 v16, v16, v4
	v_add_u32_e32 v16, v16, v5
	v_add_u32_e32 v16, v16, v6
	v_add_u32_e32 v16, v16, v7
	v_add_u32_e32 v16, v16, v8
	v_add_u32_e32 v16, v16, v9
	v_add_u32_e32 v16, v16, v10
	v_add_u32_e32 v16, v16, v11
	v_add_u32_e32 v16, v16, v12
	v_add_u32_e32 v16, v16, v13
	v_add_u32_e32 v16, v16, v14
	v_add_u32_e32 v16, v16, v15
	v_cmp_ne_u32_e32 vcc, s64, v16
	s_and_saveexec_b64 s[46:47], vcc
	s_cbranch_execz .LBB0_1167
	s_and_b32 s50, s62, 0xff
	s_mov_b64 s[48:49], -1
	s_cmp_eq_u32 s50, 0
	s_mov_b64 s[56:57], -1
	s_mov_b64 s[50:51], -1
	s_sleep 1
	s_cbranch_scc1 .LBB0_1171
	s_and_saveexec_b64 s[58:59], s[56:57]
	s_cbranch_execz .LBB0_1166
	s_branch .LBB0_1174
